# combined variant with all eight GQA K reads up front and the sixteen V reads fed two per QK MFMA gap
# speedup vs baseline: 1.0071x; 1.0008x over previous
.LBB0_580:
	ds_read_b128 v[32:35], v194
	ds_read_b128 v[36:39], v194 offset:4608
	ds_read_b128 v[96:99], v194 offset:32
	ds_read_b128 v[104:107], v194 offset:4640
	ds_read_b128 v[114:117], v194 offset:64
	ds_read_b128 v[122:125], v194 offset:4672
	ds_read_b128 v[118:121], v194 offset:96
	ds_read_b128 v[134:137], v194 offset:4704
	s_waitcnt lgkmcnt(7)
	v_mfma_f32_32x32x16_bf16 v[48:63], v[32:35], v[64:67], 0
	s_add_i32 s15, s14, 1
	s_cmp_ge_u32 s15, s37
	ds_read_b64_tr_b16 v[138:139], v218 offset:9216
	ds_read_b64_tr_b16 v[140:141], v218 offset:10240
	s_waitcnt lgkmcnt(8)
	v_mfma_f32_32x32x16_bf16 v[32:47], v[36:39], v[64:67], 0
	ds_read_b64_tr_b16 v[148:149], v218 offset:10496
	ds_read_b64_tr_b16 v[146:147], v218 offset:9472
	s_waitcnt lgkmcnt(9)
	v_mfma_f32_32x32x16_bf16 v[48:63], v[96:99], v[68:71], v[48:63]
	ds_read_b64_tr_b16 v[152:153], v218 offset:11264
	ds_read_b64_tr_b16 v[154:155], v218 offset:12288
	s_waitcnt lgkmcnt(10)
	v_mfma_f32_32x32x16_bf16 v[32:47], v[104:107], v[68:71], v[32:47]
	ds_read_b64_tr_b16 v[158:159], v218 offset:12544
	ds_read_b64_tr_b16 v[156:157], v218 offset:11520
	s_waitcnt lgkmcnt(11)
	v_mfma_f32_32x32x16_bf16 v[48:63], v[114:117], v[72:75], v[48:63]
	ds_read_b64_tr_b16 v[160:161], v218 offset:13312
	ds_read_b64_tr_b16 v[162:163], v218 offset:14336
	s_waitcnt lgkmcnt(12)
	v_mfma_f32_32x32x16_bf16 v[32:47], v[122:125], v[72:75], v[32:47]
	ds_read_b64_tr_b16 v[166:167], v218 offset:14592
	ds_read_b64_tr_b16 v[164:165], v218 offset:13568
	s_waitcnt lgkmcnt(13)
	v_mfma_f32_32x32x16_bf16 v[48:63], v[118:121], v[76:79], v[48:63]
	ds_read_b64_tr_b16 v[168:169], v218 offset:15360
	ds_read_b64_tr_b16 v[170:171], v218 offset:16384
	s_waitcnt lgkmcnt(14)
	v_mfma_f32_32x32x16_bf16 v[32:47], v[134:137], v[76:79], v[32:47]
	ds_read_b64_tr_b16 v[174:175], v218 offset:16640
	ds_read_b64_tr_b16 v[172:173], v218 offset:15616
	s_nop 10
	v_exp_f32_e32 v96, v48
	v_exp_f32_e32 v97, v49
	v_exp_f32_e32 v98, v50
	v_exp_f32_e32 v99, v51
	v_exp_f32_e32 v104, v52
	v_exp_f32_e32 v105, v53
	v_exp_f32_e32 v106, v54
	v_exp_f32_e32 v109, v32
	v_exp_f32_e32 v110, v33
	v_exp_f32_e32 v111, v34
	v_exp_f32_e32 v114, v35
	v_exp_f32_e32 v107, v55
	v_cvt_pk_bf16_f32 v32, v96, v97
	v_cvt_pk_bf16_f32 v33, v98, v99
	v_cvt_pk_bf16_f32 v34, v104, v105
	v_cvt_pk_bf16_f32 v35, v106, v107
	v_exp_f32_e32 v115, v36
	s_waitcnt lgkmcnt(14)
	v_mfma_f32_32x32x16_bf16 v[0:15], v[138:141], v[32:35], v[0:15]
	v_exp_f32_e32 v116, v37
	v_exp_f32_e32 v117, v38
	v_exp_f32_e32 v118, v39
	v_exp_f32_e32 v119, v56
	v_exp_f32_e32 v120, v57
	v_exp_f32_e32 v126, v58
	v_exp_f32_e32 v125, v59
	s_waitcnt lgkmcnt(12)
	v_mfma_f32_32x32x16_bf16 v[16:31], v[146:149], v[32:35], v[16:31]
	v_exp_f32_e32 v124, v60
	v_exp_f32_e32 v123, v61
	v_exp_f32_e32 v122, v62
	v_exp_f32_e32 v121, v63
	v_cvt_pk_bf16_f32 v36, v109, v110
	v_cvt_pk_bf16_f32 v37, v111, v114
	v_cvt_pk_bf16_f32 v38, v115, v116
	v_cvt_pk_bf16_f32 v39, v117, v118
	v_cvt_pk_bf16_f32 v32, v119, v120
	v_cvt_pk_bf16_f32 v33, v126, v125
	v_cvt_pk_bf16_f32 v34, v124, v123
	v_cvt_pk_bf16_f32 v35, v122, v121
	v_exp_f32_e32 v138, v40
	s_waitcnt lgkmcnt(10)
	v_mfma_f32_32x32x16_bf16 v[0:15], v[152:155], v[32:35], v[0:15]
	v_exp_f32_e32 v137, v41
	v_exp_f32_e32 v136, v42
	v_exp_f32_e32 v134, v43
	v_exp_f32_e32 v131, v44
	v_exp_f32_e32 v135, v45
	v_exp_f32_e32 v133, v46
	v_exp_f32_e32 v127, v47
	s_waitcnt lgkmcnt(8)
	v_mfma_f32_32x32x16_bf16 v[16:31], v[156:159], v[32:35], v[16:31]
	v_cvt_pk_bf16_f32 v32, v138, v137
	v_cvt_pk_bf16_f32 v33, v136, v134
	v_cvt_pk_bf16_f32 v34, v131, v135
	v_cvt_pk_bf16_f32 v35, v133, v127
	s_waitcnt lgkmcnt(6)
	v_mfma_f32_32x32x16_bf16 v[0:15], v[160:163], v[36:39], v[0:15]
	s_waitcnt lgkmcnt(4)
	v_mfma_f32_32x32x16_bf16 v[16:31], v[164:167], v[36:39], v[16:31]
	s_waitcnt lgkmcnt(2)
	v_mfma_f32_32x32x16_bf16 v[0:15], v[168:171], v[32:35], v[0:15]
	s_waitcnt lgkmcnt(0)
	v_mfma_f32_32x32x16_bf16 v[16:31], v[172:175], v[32:35], v[16:31]
	s_cbranch_scc1 .LBB0_582
	s_cmp_ge_u32 s13, s37
	s_cbranch_scc1 .Lgqa_w0_tail
	s_waitcnt vmcnt(3)
	ds_write_b128 v193, v[88:91] offset:17408
	s_waitcnt vmcnt(2)
	ds_write_b128 v219, v[92:95] offset:26624
	s_branch .LBB0_582

.LBB0_584:
	ds_read_b128 v[32:35], v194 offset:17408
	ds_read_b128 v[36:39], v194 offset:22016
	ds_read_b128 v[140:143], v194 offset:17440
	ds_read_b128 v[146:149], v194 offset:22048
	ds_read_b128 v[152:155], v194 offset:17472
	ds_read_b128 v[160:163], v194 offset:22080
	ds_read_b128 v[156:159], v194 offset:17504
	ds_read_b128 v[164:167], v194 offset:22112
	s_waitcnt lgkmcnt(7)
	v_mfma_f32_32x32x16_bf16 v[48:63], v[32:35], v[64:67], 0
	v_add_f32_e32 v222, v96, v97
	v_add_f32_e32 v223, v109, v110
	v_add_f32_e32 v222, v98, v222
	v_add_f32_e32 v223, v111, v223
	s_andn2_b64 vcc, exec, s[10:11]
	ds_read_b64_tr_b16 v[168:169], v218 offset:26624
	ds_read_b64_tr_b16 v[170:171], v218 offset:27648
	s_waitcnt lgkmcnt(8)
	v_mfma_f32_32x32x16_bf16 v[32:47], v[36:39], v[64:67], 0
	v_add_f32_e32 v222, v99, v222
	v_add_f32_e32 v223, v114, v223
	v_add_f32_e32 v222, v104, v222
	v_add_f32_e32 v223, v115, v223
	ds_read_b64_tr_b16 v[174:175], v218 offset:27904
	ds_read_b64_tr_b16 v[172:173], v218 offset:26880
	s_waitcnt lgkmcnt(9)
	v_mfma_f32_32x32x16_bf16 v[48:63], v[140:143], v[68:71], v[48:63]
	v_add_f32_e32 v222, v105, v222
	v_add_f32_e32 v223, v116, v223
	v_add_f32_e32 v222, v106, v222
	v_add_f32_e32 v223, v117, v223
	ds_read_b64_tr_b16 v[176:177], v218 offset:28672
	ds_read_b64_tr_b16 v[178:179], v218 offset:29696
	s_waitcnt lgkmcnt(10)
	v_mfma_f32_32x32x16_bf16 v[32:47], v[146:149], v[68:71], v[32:47]
	v_add_f32_e32 v222, v107, v222
	v_add_f32_e32 v223, v118, v223
	v_add_f32_e32 v222, v119, v222
	v_add_f32_e32 v223, v138, v223
	ds_read_b64_tr_b16 v[182:183], v218 offset:29952
	ds_read_b64_tr_b16 v[180:181], v218 offset:28928
	s_waitcnt lgkmcnt(11)
	v_mfma_f32_32x32x16_bf16 v[48:63], v[152:155], v[72:75], v[48:63]
	v_add_f32_e32 v222, v120, v222
	v_add_f32_e32 v223, v137, v223
	v_add_f32_e32 v222, v126, v222
	v_add_f32_e32 v223, v136, v223
	ds_read_b64_tr_b16 v[184:185], v218 offset:30720
	ds_read_b64_tr_b16 v[186:187], v218 offset:31744
	s_waitcnt lgkmcnt(12)
	v_mfma_f32_32x32x16_bf16 v[32:47], v[160:163], v[72:75], v[32:47]
	v_add_f32_e32 v222, v125, v222
	v_add_f32_e32 v223, v134, v223
	v_add_f32_e32 v222, v124, v222
	v_add_f32_e32 v223, v131, v223
	ds_read_b64_tr_b16 v[190:191], v218 offset:32000
	ds_read_b64_tr_b16 v[188:189], v218 offset:30976
	s_waitcnt lgkmcnt(13)
	v_mfma_f32_32x32x16_bf16 v[48:63], v[156:159], v[76:79], v[48:63]
	v_add_f32_e32 v222, v123, v222
	v_add_f32_e32 v223, v135, v223
	v_add_f32_e32 v222, v122, v222
	v_add_f32_e32 v223, v133, v223
	ds_read_b64_tr_b16 v[196:197], v218 offset:32768
	ds_read_b64_tr_b16 v[198:199], v218 offset:33792
	s_waitcnt lgkmcnt(14)
	v_mfma_f32_32x32x16_bf16 v[32:47], v[164:167], v[76:79], v[32:47]
	ds_read_b64_tr_b16 v[202:203], v218 offset:34048
	ds_read_b64_tr_b16 v[200:201], v218 offset:33024
	v_add_f32_e32 v222, v121, v222
	v_add_f32_e32 v223, v127, v223
	v_add_f32_e32 v222, v222, v223
	s_nop 10
	v_exp_f32_e32 v48, v48
	v_exp_f32_e32 v141, v58
	v_exp_f32_e32 v140, v59
	v_exp_f32_e32 v60, v60
	v_exp_f32_e32 v59, v61
	v_exp_f32_e32 v58, v62
	v_exp_f32_e32 v139, v32
	v_exp_f32_e32 v32, v49
	v_exp_f32_e32 v49, v33
	v_exp_f32_e32 v33, v50
	v_exp_f32_e32 v50, v34
	v_exp_f32_e32 v34, v51
	v_exp_f32_e32 v51, v35
	v_exp_f32_e32 v35, v52
	v_exp_f32_e32 v52, v36
	v_exp_f32_e32 v36, v53
	v_exp_f32_e32 v53, v37
	v_exp_f32_e32 v37, v54
	v_exp_f32_e32 v54, v38
	v_exp_f32_e32 v38, v55
	v_cvt_pk_bf16_f32 v146, v48, v32
	v_cvt_pk_bf16_f32 v147, v33, v34
	v_cvt_pk_bf16_f32 v148, v35, v36
	v_cvt_pk_bf16_f32 v149, v37, v38
	v_exp_f32_e32 v39, v39
	s_waitcnt lgkmcnt(14)
	v_mfma_f32_32x32x16_bf16 v[0:15], v[168:171], v[146:149], v[0:15]
	v_exp_f32_e32 v55, v56
	v_exp_f32_e32 v56, v57
	v_exp_f32_e32 v57, v63
	v_cvt_pk_bf16_f32 v152, v139, v49
	v_cvt_pk_bf16_f32 v153, v50, v51
	v_cvt_pk_bf16_f32 v154, v52, v53
	v_cvt_pk_bf16_f32 v155, v54, v39
	s_waitcnt lgkmcnt(12)
	v_mfma_f32_32x32x16_bf16 v[16:31], v[172:175], v[146:149], v[16:31]
	v_cvt_pk_bf16_f32 v146, v55, v56
	v_cvt_pk_bf16_f32 v147, v141, v140
	v_cvt_pk_bf16_f32 v148, v60, v59
	v_cvt_pk_bf16_f32 v149, v58, v57
	v_exp_f32_e32 v63, v40
	v_exp_f32_e32 v62, v41
	v_exp_f32_e32 v61, v42
	s_waitcnt lgkmcnt(10)
	v_mfma_f32_32x32x16_bf16 v[0:15], v[176:179], v[146:149], v[0:15]
	v_exp_f32_e32 v43, v43
	v_exp_f32_e32 v41, v44
	v_exp_f32_e32 v44, v45
	v_exp_f32_e32 v42, v46
	v_exp_f32_e32 v40, v47
	s_waitcnt lgkmcnt(8)
	v_mfma_f32_32x32x16_bf16 v[16:31], v[180:183], v[146:149], v[16:31]
	v_add_f32_e32 v224, v48, v32
	v_add_f32_e32 v225, v139, v49
	v_add_f32_e32 v224, v33, v224
	v_add_f32_e32 v225, v50, v225
	v_add_f32_e32 v224, v34, v224
	v_add_f32_e32 v225, v51, v225
	v_add_f32_e32 v224, v35, v224
	v_add_f32_e32 v225, v52, v225
	v_cvt_pk_bf16_f32 v146, v63, v62
	v_cvt_pk_bf16_f32 v147, v61, v43
	v_cvt_pk_bf16_f32 v148, v41, v44
	v_cvt_pk_bf16_f32 v149, v42, v40
	s_waitcnt lgkmcnt(6)
	v_mfma_f32_32x32x16_bf16 v[0:15], v[184:187], v[152:155], v[0:15]
	v_add_f32_e32 v224, v36, v224
	v_add_f32_e32 v225, v53, v225
	v_add_f32_e32 v224, v37, v224
	v_add_f32_e32 v225, v54, v225
	v_add_f32_e32 v224, v38, v224
	v_add_f32_e32 v225, v39, v225
	v_add_f32_e32 v224, v55, v224
	v_add_f32_e32 v225, v63, v225
	s_waitcnt lgkmcnt(4)
	v_mfma_f32_32x32x16_bf16 v[16:31], v[188:191], v[152:155], v[16:31]
	v_add_f32_e32 v224, v56, v224
	v_add_f32_e32 v225, v62, v225
	v_add_f32_e32 v224, v141, v224
	v_add_f32_e32 v225, v61, v225
	v_add_f32_e32 v224, v140, v224
	v_add_f32_e32 v225, v43, v225
	v_add_f32_e32 v224, v60, v224
	v_add_f32_e32 v225, v41, v225
	s_waitcnt lgkmcnt(2)
	v_mfma_f32_32x32x16_bf16 v[0:15], v[196:199], v[146:149], v[0:15]
	v_add_f32_e32 v224, v59, v224
	v_add_f32_e32 v225, v44, v225
	v_add_f32_e32 v224, v58, v224
	v_add_f32_e32 v225, v42, v225
	v_add_f32_e32 v224, v57, v224
	v_add_f32_e32 v225, v40, v225
	v_add_f32_e32 v224, v224, v225
	s_waitcnt lgkmcnt(0)
	v_mfma_f32_32x32x16_bf16 v[16:31], v[200:203], v[146:149], v[16:31]
	s_cbranch_vccnz .LBB0_586
	s_cmp_ge_u32 s14, s12
	s_cbranch_scc1 .Lgqa_w1_tail
	s_waitcnt vmcnt(3)
	ds_write_b128 v193, v[80:83]
	s_waitcnt vmcnt(2)
	ds_write_b128 v219, v[84:87] offset:9216
	s_branch .LBB0_586
